# gla_scan moved to workgroups 128-255 (less loaded in the uq/ukv phase); plus norm-phase partial loads batched
# speedup vs baseline: 1.0046x; 1.0046x over previous
; __device__ __forceinline__ void gla_scan(CArgs& a, int dup) {
;     float* KVS = (float*)(a.ws + WS_KVS); float* KVO = dup ? (float*)a.out + (10u << 20) : KVS; const float* DEC = (const float*)(a.ws + WS_DEC);
;     int tid = threadIdx.x; asm volatile("" : "+v"(tid));
;     for (int g = blockIdx.x * 512 + tid; g < 32 * 2048; g += gridDim.x * 512) {
;         const int seq = g >> 11, el = (g & 2047) * 4, d = el & 63, b = seq >> 3, h = (seq >> 1) & 3, dir = seq & 1;
.LBB0_298:
	v_readlane_b32 s4, v255, 52
	s_cmp_eq_u32 s4, 3
	s_cbranch_scc0 .LBB0_305
	v_mov_b32_e32 v0, v201
	v_readlane_b32 s4, v254, 6
	s_nop 3
	s_add_i32 s4, s4, 0xffff0000
	s_nop 1
	v_add_u32_e32 v139, s4, v0
	s_mov_b32 s4, 0x10000
	v_cmp_gt_u32_e32 vcc, s4, v139
	s_and_saveexec_b64 s[8:9], vcc
	s_cbranch_execz .LBB0_304
	s_waitcnt lgkmcnt(0)
	s_add_u32 s12, s56, 0x26300000
	s_addc_u32 s13, s57, 0
	s_add_u32 s36, s56, 0x2a700000
	s_addc_u32 s37, s57, 0
	s_mov_b64 s[38:39], 0
